# v50 + kpair MFMA order in the in-projection loop too (same-accumulator k0,k1 back to back in all three 1BAR loops)
# speedup vs baseline: 1.0069x; 1.0029x over previous
; #define PG8_STAGE(bufoff, gbase, voff) do { _Pragma("unroll") for (int _i = 0; _i < 2; ++_i) \
;         __builtin_amdgcn_global_load_lds((const unsigned*)((const char*)(gbase) + (voff)[_i]), (PG8_LAS unsigned*)(lds + (bufoff) + ldsw + _i * 8192), 16, 0, 0); } while (0)
; #define PG8_LDA(dst, b, h) do { _Pragma("unroll") for (int m = 0; m < 4; ++m) _Pragma("unroll") for (int k = 0; k < 2; ++k) dst[m][k] = *(const PG8_LAS bf16x8*)(lds + PG8_SA(b, h) + aoff + m * 2048 + k * 1024); } while (0)
; #define PG8_LDB(dst, b, h) do { _Pragma("unroll") for (int n = 0; n < 2; ++n) _Pragma("unroll") for (int k = 0; k < 2; ++k) dst[n][k] = *(const PG8_LAS bf16x8*)(lds + PG8_SB(b, h) + boff + n * 2048 + k * 1024); } while (0)
; #define PG8_MMA(ai, bj, At, Bt) do { __builtin_amdgcn_s_setprio(1); _Pragma("unroll") for (int m = 0; m < 4; ++m) _Pragma("unroll") for (int n = 0; n < 2; ++n) _Pragma("unroll") for (int k = 0; k < 2; ++k) \
;         acc[ai][bj][m][n] = __builtin_amdgcn_mfma_f32_16x16x32_bf16(Bt[n][k], At[m][k], acc[ai][bj][m][n], 0, 0, 0); __builtin_amdgcn_s_setprio(0); } while (0)
; template <class Epi, class Sched, bool ALIGN_EPI = false, bool SP2 = false>
; __device__ __forceinline__ void gemm_phase(PG8_LAS unsigned char* lds, const Gemm g, const Sched& S, const Epi& E) {
;     ...
;         for (int t = 0; t < nt; t += 2) {
;             const bool last = (t == nt - 2);
;             const char* a1 = cA + (size_t)(t + 1) * kstep;
;             const char* a2 = last ? nA : cA + (size_t)(t + 2) * kstep; const char* b2 = last ? nB : cB + (size_t)(t + 2) * kstep;
;             const char* a3 = a2 + kstep; const char* b3 = b2 + kstep;
;             if (last && has_next) S.a_ready(nxt);
;             if constexpr (Epi::MIDK) { if (t == (nt >> 1)) { E.midk(acc, wr, fr); asm volatile("s_waitcnt lgkmcnt(0)" ::: "memory"); } }
;             if constexpr (SP2) {
;             PG8_LDB(B0, 0, 0); PG8_LDB(B1, 0, 1); PG8_SCHED; PG8_LDA(At, 0, 0); PG8_STAGE(PG8_SA(1, 1), a1 + hstep, voffA);
;             PG8_WAIT_V(8); PG8_WAIT_L(0); PG8_BAR; PG8_MMA(0, 0, At, B0); PG8_MMA(0, 1, At, B1); PG8_BAR; PG8_SCHED;
;             PG8_LDA(At, 0, 1); PG8_STAGE(PG8_SB(0, 0), b2, voffB); PG8_STAGE(PG8_SB(0, 1), b2 + hstep, voffB); PG8_STAGE(PG8_SA(0, 0), a2, voffA);
;             PG8_WAIT_V(8); PG8_WAIT_L(0); PG8_BAR; PG8_MMA(1, 0, At, B0); PG8_MMA(1, 1, At, B1); PG8_BAR; PG8_SCHED;
.LBB0_349:
	ds_read_b128 v[150:153], v169
	ds_read_b128 v[154:157], v169 offset:1024
	ds_read_b128 v[158:161], v169 offset:2048
	ds_read_b128 v[162:165], v169 offset:3072
	ds_read_b128 v[174:177], v170
	ds_read_b128 v[178:181], v170 offset:1024
	ds_read_b128 v[182:185], v170 offset:2048
	ds_read_b128 v[186:189], v170 offset:3072
	s_add_u32 s0, s88, 0xfff00080
	s_addc_u32 s1, s89, -1
	s_cmp_eq_u32 s23, 60
	s_cselect_b32 s93, s51, s1
	s_cselect_b32 s92, s50, s0
	s_cselect_b32 s91, s53, s21
	s_cselect_b32 s90, s52, s9
	ds_read_b128 v[190:193], v171
	ds_read_b128 v[196:199], v171 offset:1024
	ds_read_b128 v[200:203], v171 offset:2048
	ds_read_b128 v[204:207], v171 offset:3072
	ds_read_b128 v[208:211], v171 offset:4096
	ds_read_b128 v[212:215], v171 offset:5120
	ds_read_b128 v[220:223], v171 offset:6144
	ds_read_b128 v[224:227], v171 offset:7168
	s_add_u32 s0, s88, 0xfff00000
	s_addc_u32 s1, s89, -1
	s_add_i32 m0, s27, 0x8000
	s_nop 0
	global_load_lds_dwordx4 v134, s[0:1]
	s_add_i32 m0, s27, 0xa000
	s_nop 0
	global_load_lds_dwordx4 v138, s[0:1]
	s_add_i32 m0, s27, 0xc000
	s_nop 0
	global_load_lds_dwordx4 v134, s[88:89]
	s_add_i32 m0, s27, 0xe000
	s_nop 0
	global_load_lds_dwordx4 v138, s[88:89]
	s_waitcnt lgkmcnt(0)
	s_setprio 1
	v_mfma_f32_16x16x32_bf16 v[38:41], v[150:153], v[190:193], v[38:41]
	v_mfma_f32_16x16x32_bf16 v[38:41], v[154:157], v[196:199], v[38:41]
	v_mfma_f32_16x16x32_bf16 v[30:33], v[158:161], v[190:193], v[30:33]
	v_mfma_f32_16x16x32_bf16 v[30:33], v[162:165], v[196:199], v[30:33]
	v_mfma_f32_16x16x32_bf16 v[130:133], v[150:153], v[200:203], v[130:133]
	v_mfma_f32_16x16x32_bf16 v[130:133], v[154:157], v[204:207], v[130:133]
	v_mfma_f32_16x16x32_bf16 v[126:129], v[158:161], v[200:203], v[126:129]
	v_mfma_f32_16x16x32_bf16 v[126:129], v[162:165], v[204:207], v[126:129]
	v_mfma_f32_16x16x32_bf16 v[114:117], v[150:153], v[208:211], v[114:117]
	v_mfma_f32_16x16x32_bf16 v[114:117], v[154:157], v[212:215], v[114:117]
	v_mfma_f32_16x16x32_bf16 v[110:113], v[158:161], v[208:211], v[110:113]
	v_mfma_f32_16x16x32_bf16 v[110:113], v[162:165], v[212:215], v[110:113]
	v_mfma_f32_16x16x32_bf16 v[98:101], v[150:153], v[220:223], v[98:101]
	v_mfma_f32_16x16x32_bf16 v[98:101], v[154:157], v[224:227], v[98:101]
	v_mfma_f32_16x16x32_bf16 v[94:97], v[158:161], v[220:223], v[94:97]
	v_mfma_f32_16x16x32_bf16 v[94:97], v[162:165], v[224:227], v[94:97]
	v_mfma_f32_16x16x32_bf16 v[50:53], v[174:177], v[190:193], v[50:53]
	v_mfma_f32_16x16x32_bf16 v[50:53], v[178:181], v[196:199], v[50:53]
	v_mfma_f32_16x16x32_bf16 v[46:49], v[182:185], v[190:193], v[46:49]
	v_mfma_f32_16x16x32_bf16 v[46:49], v[186:189], v[196:199], v[46:49]
	v_mfma_f32_16x16x32_bf16 v[122:125], v[174:177], v[200:203], v[122:125]
	v_mfma_f32_16x16x32_bf16 v[122:125], v[178:181], v[204:207], v[122:125]
	v_mfma_f32_16x16x32_bf16 v[118:121], v[182:185], v[200:203], v[118:121]
	v_mfma_f32_16x16x32_bf16 v[118:121], v[186:189], v[204:207], v[118:121]
	v_mfma_f32_16x16x32_bf16 v[106:109], v[174:177], v[208:211], v[106:109]
	v_mfma_f32_16x16x32_bf16 v[106:109], v[178:181], v[212:215], v[106:109]
	v_mfma_f32_16x16x32_bf16 v[102:105], v[182:185], v[208:211], v[102:105]
	v_mfma_f32_16x16x32_bf16 v[102:105], v[186:189], v[212:215], v[102:105]
	v_mfma_f32_16x16x32_bf16 v[90:93], v[174:177], v[220:223], v[90:93]
	v_mfma_f32_16x16x32_bf16 v[90:93], v[178:181], v[224:227], v[90:93]
	v_mfma_f32_16x16x32_bf16 v[86:89], v[182:185], v[220:223], v[86:89]
	v_mfma_f32_16x16x32_bf16 v[86:89], v[186:189], v[224:227], v[86:89]
	s_setprio 0
	s_waitcnt vmcnt(8)
	s_barrier
	ds_read_b128 v[190:193], v171 offset:16384
	ds_read_b128 v[196:199], v171 offset:17408
	ds_read_b128 v[200:203], v171 offset:18432
	ds_read_b128 v[204:207], v171 offset:19456
	ds_read_b128 v[208:211], v171 offset:20480
	ds_read_b128 v[212:215], v171 offset:21504
	ds_read_b128 v[220:223], v171 offset:22528
	ds_read_b128 v[224:227], v171 offset:23552
	s_add_u32 vcc_lo, s90, 0x100000
	s_addc_u32 vcc_hi, s91, 0
	s_add_i32 m0, s27, 0x10000
	s_nop 0
	global_load_lds_dwordx4 v136, s[90:91]
	s_add_i32 m0, s27, 0x12000
	s_nop 0
	global_load_lds_dwordx4 v140, s[90:91]
	s_add_i32 m0, s27, 0x14000
	s_nop 0
	global_load_lds_dwordx4 v136, vcc
	s_add_i32 m0, s27, 0x16000
	s_nop 0
	global_load_lds_dwordx4 v140, vcc
	s_waitcnt lgkmcnt(0)
	s_setprio 1
	v_mfma_f32_16x16x32_bf16 v[82:85], v[150:153], v[190:193], v[82:85]
	v_mfma_f32_16x16x32_bf16 v[82:85], v[154:157], v[196:199], v[82:85]
	v_mfma_f32_16x16x32_bf16 v[78:81], v[158:161], v[190:193], v[78:81]
	v_mfma_f32_16x16x32_bf16 v[78:81], v[162:165], v[196:199], v[78:81]
	v_mfma_f32_16x16x32_bf16 v[66:69], v[150:153], v[200:203], v[66:69]
	v_mfma_f32_16x16x32_bf16 v[66:69], v[154:157], v[204:207], v[66:69]
	v_mfma_f32_16x16x32_bf16 v[62:65], v[158:161], v[200:203], v[62:65]
	v_mfma_f32_16x16x32_bf16 v[62:65], v[162:165], v[204:207], v[62:65]
	v_mfma_f32_16x16x32_bf16 v[42:45], v[150:153], v[208:211], v[42:45]
	v_mfma_f32_16x16x32_bf16 v[42:45], v[154:157], v[212:215], v[42:45]
	v_mfma_f32_16x16x32_bf16 v[34:37], v[158:161], v[208:211], v[34:37]
	v_mfma_f32_16x16x32_bf16 v[34:37], v[162:165], v[212:215], v[34:37]
	v_mfma_f32_16x16x32_bf16 v[18:21], v[150:153], v[220:223], v[18:21]
	v_mfma_f32_16x16x32_bf16 v[18:21], v[154:157], v[224:227], v[18:21]
	v_mfma_f32_16x16x32_bf16 v[14:17], v[158:161], v[220:223], v[14:17]
	v_mfma_f32_16x16x32_bf16 v[14:17], v[162:165], v[224:227], v[14:17]
	v_mfma_f32_16x16x32_bf16 v[74:77], v[174:177], v[190:193], v[74:77]
	v_mfma_f32_16x16x32_bf16 v[74:77], v[178:181], v[196:199], v[74:77]
	v_mfma_f32_16x16x32_bf16 v[70:73], v[182:185], v[190:193], v[70:73]
	v_mfma_f32_16x16x32_bf16 v[70:73], v[186:189], v[196:199], v[70:73]
	v_mfma_f32_16x16x32_bf16 v[58:61], v[174:177], v[200:203], v[58:61]
	v_mfma_f32_16x16x32_bf16 v[58:61], v[178:181], v[204:207], v[58:61]
	v_mfma_f32_16x16x32_bf16 v[54:57], v[182:185], v[200:203], v[54:57]
	v_mfma_f32_16x16x32_bf16 v[54:57], v[186:189], v[204:207], v[54:57]
	v_mfma_f32_16x16x32_bf16 v[26:29], v[174:177], v[208:211], v[26:29]
	v_mfma_f32_16x16x32_bf16 v[26:29], v[178:181], v[212:215], v[26:29]
	v_mfma_f32_16x16x32_bf16 v[22:25], v[182:185], v[208:211], v[22:25]
	v_mfma_f32_16x16x32_bf16 v[22:25], v[186:189], v[212:215], v[22:25]
	v_mfma_f32_16x16x32_bf16 v[10:13], v[174:177], v[220:223], v[10:13]
	v_mfma_f32_16x16x32_bf16 v[10:13], v[178:181], v[224:227], v[10:13]
	v_mfma_f32_16x16x32_bf16 v[4:7], v[182:185], v[220:223], v[6:9]
	v_mfma_f32_16x16x32_bf16 v[4:7], v[186:189], v[224:227], v[4:7]
	s_setprio 0
	s_waitcnt vmcnt(6)
	s_barrier
; #define PG8_STAGE(bufoff, gbase, voff) do { _Pragma("unroll") for (int _i = 0; _i < 2; ++_i) \
;         __builtin_amdgcn_global_load_lds((const unsigned*)((const char*)(gbase) + (voff)[_i]), (PG8_LAS unsigned*)(lds + (bufoff) + ldsw + _i * 8192), 16, 0, 0); } while (0)
; #define PG8_LDA(dst, b, h) do { _Pragma("unroll") for (int m = 0; m < 4; ++m) _Pragma("unroll") for (int k = 0; k < 2; ++k) dst[m][k] = *(const PG8_LAS bf16x8*)(lds + PG8_SA(b, h) + aoff + m * 2048 + k * 1024); } while (0)
; #define PG8_LDB(dst, b, h) do { _Pragma("unroll") for (int n = 0; n < 2; ++n) _Pragma("unroll") for (int k = 0; k < 2; ++k) dst[n][k] = *(const PG8_LAS bf16x8*)(lds + PG8_SB(b, h) + boff + n * 2048 + k * 1024); } while (0)
; #define PG8_MMA(ai, bj, At, Bt) do { __builtin_amdgcn_s_setprio(1); _Pragma("unroll") for (int m = 0; m < 4; ++m) _Pragma("unroll") for (int n = 0; n < 2; ++n) _Pragma("unroll") for (int k = 0; k < 2; ++k) \
;         acc[ai][bj][m][n] = __builtin_amdgcn_mfma_f32_16x16x32_bf16(Bt[n][k], At[m][k], acc[ai][bj][m][n], 0, 0, 0); __builtin_amdgcn_s_setprio(0); } while (0)
; #define PG8_WAIT_V(n) asm volatile("s_waitcnt vmcnt(" #n ")" ::: "memory")
; #define PG8_WAIT_L(n) asm volatile("s_waitcnt lgkmcnt(" #n ")" ::: "memory")
; #define PG8_BAR __builtin_amdgcn_s_barrier()
; #define PG8_SCHED __builtin_amdgcn_sched_barrier(0)
; template <class Epi, class Sched, bool ALIGN_EPI = false, bool SP2 = false>
; __device__ __forceinline__ void gemm_phase(PG8_LAS unsigned char* lds, const Gemm g, const Sched& S, const Epi& E) {
;     ...
;             PG8_LDB(B0, 1, 0); PG8_LDB(B1, 1, 1); PG8_SCHED; PG8_LDA(At, 1, 0); PG8_STAGE(PG8_SA(0, 1), a2 + hstep, voffA);
;             PG8_WAIT_V(8); PG8_WAIT_L(0); PG8_BAR; PG8_MMA(0, 0, At, B0); PG8_MMA(0, 1, At, B1); PG8_BAR; PG8_SCHED;
;             PG8_LDA(At, 1, 1); PG8_STAGE(PG8_SB(1, 0), b3, voffB); PG8_STAGE(PG8_SB(1, 1), b3 + hstep, voffB); PG8_STAGE(PG8_SA(1, 0), a3, voffA);
;             PG8_WAIT_V(8); PG8_WAIT_L(0); PG8_BAR; PG8_MMA(1, 0, At, B0); PG8_MMA(1, 1, At, B1); PG8_BAR; PG8_SCHED;
	s_add_i32 s0, 0, 0x18000
	v_add_u32_e32 v3, s0, v167
	s_add_i32 s1, 0, 0x1c000
	ds_read_b128 v[150:153], v3
	ds_read_b128 v[154:157], v3 offset:1024
	ds_read_b128 v[158:161], v3 offset:2048
	ds_read_b128 v[162:165], v3 offset:3072
	v_add_u32_e32 v3, s1, v167
	ds_read_b128 v[174:177], v3
	ds_read_b128 v[178:181], v3 offset:1024
	ds_read_b128 v[182:185], v3 offset:2048
	ds_read_b128 v[186:189], v3 offset:3072
	ds_read_b128 v[190:193], v171 offset:32768
	ds_read_b128 v[196:199], v171 offset:33792
	ds_read_b128 v[200:203], v171 offset:34816
	ds_read_b128 v[204:207], v171 offset:35840
	ds_read_b128 v[208:211], v171 offset:36864
	ds_read_b128 v[212:215], v171 offset:37888
	ds_read_b128 v[220:223], v171 offset:38912
	ds_read_b128 v[224:227], v171 offset:39936
	s_add_u32 vcc_lo, s92, 0x100000
	s_addc_u32 vcc_hi, s93, 0
	s_mov_b32 m0, s27
	s_nop 0
	global_load_lds_dwordx4 v134, s[92:93]
	s_add_i32 m0, s27, 0x2000
	s_nop 0
	global_load_lds_dwordx4 v138, s[92:93]
	s_add_i32 m0, s27, 0x4000
	s_nop 0
	global_load_lds_dwordx4 v134, vcc
	s_add_i32 m0, s27, 0x6000
	s_nop 0
	global_load_lds_dwordx4 v138, vcc
	s_waitcnt lgkmcnt(0)
	s_setprio 1
	v_mfma_f32_16x16x32_bf16 v[38:41], v[150:153], v[190:193], v[38:41]
	v_mfma_f32_16x16x32_bf16 v[38:41], v[154:157], v[196:199], v[38:41]
	v_mfma_f32_16x16x32_bf16 v[30:33], v[158:161], v[190:193], v[30:33]
	v_mfma_f32_16x16x32_bf16 v[30:33], v[162:165], v[196:199], v[30:33]
	v_mfma_f32_16x16x32_bf16 v[130:133], v[150:153], v[200:203], v[130:133]
	v_mfma_f32_16x16x32_bf16 v[130:133], v[154:157], v[204:207], v[130:133]
	v_mfma_f32_16x16x32_bf16 v[126:129], v[158:161], v[200:203], v[126:129]
	v_mfma_f32_16x16x32_bf16 v[126:129], v[162:165], v[204:207], v[126:129]
	v_mfma_f32_16x16x32_bf16 v[114:117], v[150:153], v[208:211], v[114:117]
	v_mfma_f32_16x16x32_bf16 v[114:117], v[154:157], v[212:215], v[114:117]
	v_mfma_f32_16x16x32_bf16 v[110:113], v[158:161], v[208:211], v[110:113]
	v_mfma_f32_16x16x32_bf16 v[110:113], v[162:165], v[212:215], v[110:113]
	v_mfma_f32_16x16x32_bf16 v[98:101], v[150:153], v[220:223], v[98:101]
	v_mfma_f32_16x16x32_bf16 v[98:101], v[154:157], v[224:227], v[98:101]
	v_mfma_f32_16x16x32_bf16 v[94:97], v[158:161], v[220:223], v[94:97]
	v_mfma_f32_16x16x32_bf16 v[94:97], v[162:165], v[224:227], v[94:97]
	v_mfma_f32_16x16x32_bf16 v[50:53], v[174:177], v[190:193], v[50:53]
	v_mfma_f32_16x16x32_bf16 v[50:53], v[178:181], v[196:199], v[50:53]
	v_mfma_f32_16x16x32_bf16 v[46:49], v[182:185], v[190:193], v[46:49]
	v_mfma_f32_16x16x32_bf16 v[46:49], v[186:189], v[196:199], v[46:49]
	v_mfma_f32_16x16x32_bf16 v[122:125], v[174:177], v[200:203], v[122:125]
	v_mfma_f32_16x16x32_bf16 v[122:125], v[178:181], v[204:207], v[122:125]
	v_mfma_f32_16x16x32_bf16 v[118:121], v[182:185], v[200:203], v[118:121]
	v_mfma_f32_16x16x32_bf16 v[118:121], v[186:189], v[204:207], v[118:121]
	v_mfma_f32_16x16x32_bf16 v[106:109], v[174:177], v[208:211], v[106:109]
	v_mfma_f32_16x16x32_bf16 v[106:109], v[178:181], v[212:215], v[106:109]
	v_mfma_f32_16x16x32_bf16 v[102:105], v[182:185], v[208:211], v[102:105]
	v_mfma_f32_16x16x32_bf16 v[102:105], v[186:189], v[212:215], v[102:105]
	v_mfma_f32_16x16x32_bf16 v[90:93], v[174:177], v[220:223], v[90:93]
	v_mfma_f32_16x16x32_bf16 v[90:93], v[178:181], v[224:227], v[90:93]
	v_mfma_f32_16x16x32_bf16 v[86:89], v[182:185], v[220:223], v[86:89]
	v_mfma_f32_16x16x32_bf16 v[86:89], v[186:189], v[224:227], v[86:89]
	s_setprio 0
	s_waitcnt vmcnt(8)
	s_barrier
	ds_read_b128 v[190:193], v171 offset:49152
	ds_read_b128 v[196:199], v171 offset:50176
	ds_read_b128 v[200:203], v171 offset:51200
	ds_read_b128 v[204:207], v171 offset:52224
	ds_read_b128 v[208:211], v171 offset:53248
	ds_read_b128 v[212:215], v171 offset:54272
	ds_read_b128 v[220:223], v171 offset:55296
	ds_read_b128 v[224:227], v171 offset:56320
	s_add_u32 s0, s90, 0x80
	s_addc_u32 s1, s91, 0
	s_add_u32 vcc_lo, s0, 0x100000
	s_addc_u32 vcc_hi, s1, 0
	s_add_i32 m0, s27, 0x18000
	s_nop 0
	global_load_lds_dwordx4 v136, s[0:1]
	s_add_i32 m0, s27, 0x1a000
	s_nop 0
	global_load_lds_dwordx4 v140, s[0:1]
	s_add_i32 m0, s27, 0x1c000
	s_nop 0
	global_load_lds_dwordx4 v136, vcc
	s_add_i32 m0, s27, 0x1e000
	s_nop 0
	global_load_lds_dwordx4 v140, vcc
	s_waitcnt lgkmcnt(0)
	s_setprio 1
	v_mfma_f32_16x16x32_bf16 v[82:85], v[150:153], v[190:193], v[82:85]
	v_mfma_f32_16x16x32_bf16 v[82:85], v[154:157], v[196:199], v[82:85]
	v_mfma_f32_16x16x32_bf16 v[78:81], v[158:161], v[190:193], v[78:81]
	v_mfma_f32_16x16x32_bf16 v[78:81], v[162:165], v[196:199], v[78:81]
	v_mfma_f32_16x16x32_bf16 v[66:69], v[150:153], v[200:203], v[66:69]
	v_mfma_f32_16x16x32_bf16 v[66:69], v[154:157], v[204:207], v[66:69]
	v_mfma_f32_16x16x32_bf16 v[62:65], v[158:161], v[200:203], v[62:65]
	v_mfma_f32_16x16x32_bf16 v[62:65], v[162:165], v[204:207], v[62:65]
	v_mfma_f32_16x16x32_bf16 v[42:45], v[150:153], v[208:211], v[42:45]
	v_mfma_f32_16x16x32_bf16 v[42:45], v[154:157], v[212:215], v[42:45]
	v_mfma_f32_16x16x32_bf16 v[34:37], v[158:161], v[208:211], v[34:37]
	v_mfma_f32_16x16x32_bf16 v[34:37], v[162:165], v[212:215], v[34:37]
	v_mfma_f32_16x16x32_bf16 v[18:21], v[150:153], v[220:223], v[18:21]
	v_mfma_f32_16x16x32_bf16 v[18:21], v[154:157], v[224:227], v[18:21]
	v_mfma_f32_16x16x32_bf16 v[14:17], v[158:161], v[220:223], v[14:17]
	v_mfma_f32_16x16x32_bf16 v[14:17], v[162:165], v[224:227], v[14:17]
	v_mfma_f32_16x16x32_bf16 v[74:77], v[174:177], v[190:193], v[74:77]
	v_mfma_f32_16x16x32_bf16 v[74:77], v[178:181], v[196:199], v[74:77]
	v_mfma_f32_16x16x32_bf16 v[70:73], v[182:185], v[190:193], v[70:73]
	v_mfma_f32_16x16x32_bf16 v[70:73], v[186:189], v[196:199], v[70:73]
	v_mfma_f32_16x16x32_bf16 v[58:61], v[174:177], v[200:203], v[58:61]
	v_mfma_f32_16x16x32_bf16 v[58:61], v[178:181], v[204:207], v[58:61]
	v_mfma_f32_16x16x32_bf16 v[54:57], v[182:185], v[200:203], v[54:57]
	v_mfma_f32_16x16x32_bf16 v[54:57], v[186:189], v[204:207], v[54:57]
	v_mfma_f32_16x16x32_bf16 v[26:29], v[174:177], v[208:211], v[26:29]
	v_mfma_f32_16x16x32_bf16 v[26:29], v[178:181], v[212:215], v[26:29]
	v_mfma_f32_16x16x32_bf16 v[22:25], v[182:185], v[208:211], v[22:25]
	v_mfma_f32_16x16x32_bf16 v[22:25], v[186:189], v[212:215], v[22:25]
	v_mfma_f32_16x16x32_bf16 v[8:11], v[174:177], v[220:223], v[10:13]
	v_mfma_f32_16x16x32_bf16 v[10:13], v[178:181], v[224:227], v[8:11]
	v_mfma_f32_16x16x32_bf16 v[4:7], v[182:185], v[220:223], v[4:7]
	v_mfma_f32_16x16x32_bf16 v[6:9], v[186:189], v[224:227], v[4:7]
	s_setprio 0
	s_waitcnt vmcnt(6)
	s_barrier
	s_add_i32 s23, s23, 2
	s_add_u32 s88, s88, 0x100
	s_addc_u32 s89, s89, 0
	s_add_u32 s9, s9, 0x100
	s_addc_u32 s21, s21, 0
	s_cmp_gt_u32 s23, 61
	s_cbranch_scc0 .LBB0_349
	s_branch .Lip_exit
; #define PG8_STAGE(bufoff, gbase, voff) do { _Pragma("unroll") for (int _i = 0; _i < 2; ++_i) \
;         __builtin_amdgcn_global_load_lds((const unsigned*)((const char*)(gbase) + (voff)[_i]), (PG8_LAS unsigned*)(lds + (bufoff) + ldsw + _i * 8192), 16, 0, 0); } while (0)
; #define PG8_LDA(dst, b, h) do { _Pragma("unroll") for (int m = 0; m < 4; ++m) _Pragma("unroll") for (int k = 0; k < 2; ++k) dst[m][k] = *(const PG8_LAS bf16x8*)(lds + PG8_SA(b, h) + aoff + m * 2048 + k * 1024); } while (0)
; #define PG8_LDB(dst, b, h) do { _Pragma("unroll") for (int n = 0; n < 2; ++n) _Pragma("unroll") for (int k = 0; k < 2; ++k) dst[n][k] = *(const PG8_LAS bf16x8*)(lds + PG8_SB(b, h) + boff + n * 2048 + k * 1024); } while (0)
; #define PG8_MMA(ai, bj, At, Bt) do { __builtin_amdgcn_s_setprio(1); _Pragma("unroll") for (int m = 0; m < 4; ++m) _Pragma("unroll") for (int n = 0; n < 2; ++n) _Pragma("unroll") for (int k = 0; k < 2; ++k) \
;         acc[ai][bj][m][n] = __builtin_amdgcn_mfma_f32_16x16x32_bf16(Bt[n][k], At[m][k], acc[ai][bj][m][n], 0, 0, 0); __builtin_amdgcn_s_setprio(0); } while (0)
; #define PG8_WAIT_V(n) asm volatile("s_waitcnt vmcnt(" #n ")" ::: "memory")
; #define PG8_WAIT_L(n) asm volatile("s_waitcnt lgkmcnt(" #n ")" ::: "memory")
; #define PG8_BAR __builtin_amdgcn_s_barrier()
; #define PG8_SCHED __builtin_amdgcn_sched_barrier(0)
; template <class Epi, class Sched, bool ALIGN_EPI = false, bool SP2 = false>
; __device__ __forceinline__ void gemm_phase(PG8_LAS unsigned char* lds, const Gemm g, const Sched& S, const Epi& E) {
;     ...
;             if constexpr (SP2) {
;             PG8_LDB(B0, 0, 0); PG8_LDB(B1, 0, 1); PG8_SCHED; PG8_LDA(At, 0, 0); PG8_STAGE(PG8_SA(1, 1), a1 + hstep, voffA);
;             PG8_WAIT_V(8); PG8_WAIT_L(0); PG8_BAR; PG8_MMA(0, 0, At, B0); PG8_MMA(0, 1, At, B1); PG8_BAR; PG8_SCHED;
.Lip_h1:
	ds_read_b128 v[150:153], v169
	ds_read_b128 v[154:157], v169 offset:1024
	ds_read_b128 v[158:161], v169 offset:2048
	ds_read_b128 v[162:165], v169 offset:3072
	ds_read_b128 v[174:177], v170
	ds_read_b128 v[178:181], v170 offset:1024
	ds_read_b128 v[182:185], v170 offset:2048
	ds_read_b128 v[186:189], v170 offset:3072
	s_add_u32 s0, s88, 0xfff00080
	s_addc_u32 s1, s89, -1
	s_cmp_eq_u32 s23, 60
	s_cselect_b32 s93, s51, s1
	s_cselect_b32 s92, s50, s0
	s_cselect_b32 s91, s53, s21
	s_cselect_b32 s90, s52, s9
	ds_read_b128 v[190:193], v171
	ds_read_b128 v[196:199], v171 offset:1024
	ds_read_b128 v[200:203], v171 offset:2048
	ds_read_b128 v[204:207], v171 offset:3072
	ds_read_b128 v[208:211], v171 offset:4096
	ds_read_b128 v[212:215], v171 offset:5120
	ds_read_b128 v[220:223], v171 offset:6144
	ds_read_b128 v[224:227], v171 offset:7168
	s_add_u32 s0, s88, 0xfff00000
	s_addc_u32 s1, s89, -1
	s_add_i32 m0, s27, 0x8000
	s_nop 0
	global_load_lds_dwordx4 v134, s[0:1]
	s_add_i32 m0, s27, 0xa000
	s_nop 0
	global_load_lds_dwordx4 v138, s[0:1]
	s_add_i32 m0, s27, 0xc000
	s_nop 0
	global_load_lds_dwordx4 v134, s[88:89]
	s_add_i32 m0, s27, 0xe000
	s_nop 0
	global_load_lds_dwordx4 v138, s[88:89]
	s_sleep 2
	s_waitcnt lgkmcnt(0)
	s_waitcnt vmcnt(8)
	s_barrier
	s_setprio 2
	v_mfma_f32_16x16x32_bf16 v[38:41], v[150:153], v[190:193], v[38:41]
	v_mfma_f32_16x16x32_bf16 v[38:41], v[154:157], v[196:199], v[38:41]
	v_mfma_f32_16x16x32_bf16 v[30:33], v[158:161], v[190:193], v[30:33]
	v_mfma_f32_16x16x32_bf16 v[30:33], v[162:165], v[196:199], v[30:33]
	v_mfma_f32_16x16x32_bf16 v[130:133], v[150:153], v[200:203], v[130:133]
	v_mfma_f32_16x16x32_bf16 v[130:133], v[154:157], v[204:207], v[130:133]
	v_mfma_f32_16x16x32_bf16 v[126:129], v[158:161], v[200:203], v[126:129]
	v_mfma_f32_16x16x32_bf16 v[126:129], v[162:165], v[204:207], v[126:129]
	v_mfma_f32_16x16x32_bf16 v[114:117], v[150:153], v[208:211], v[114:117]
	v_mfma_f32_16x16x32_bf16 v[114:117], v[154:157], v[212:215], v[114:117]
	v_mfma_f32_16x16x32_bf16 v[110:113], v[158:161], v[208:211], v[110:113]
	v_mfma_f32_16x16x32_bf16 v[110:113], v[162:165], v[212:215], v[110:113]
	v_mfma_f32_16x16x32_bf16 v[98:101], v[150:153], v[220:223], v[98:101]
	v_mfma_f32_16x16x32_bf16 v[98:101], v[154:157], v[224:227], v[98:101]
	v_mfma_f32_16x16x32_bf16 v[94:97], v[158:161], v[220:223], v[94:97]
	v_mfma_f32_16x16x32_bf16 v[94:97], v[162:165], v[224:227], v[94:97]
	v_mfma_f32_16x16x32_bf16 v[50:53], v[174:177], v[190:193], v[50:53]
	v_mfma_f32_16x16x32_bf16 v[50:53], v[178:181], v[196:199], v[50:53]
	v_mfma_f32_16x16x32_bf16 v[46:49], v[182:185], v[190:193], v[46:49]
	v_mfma_f32_16x16x32_bf16 v[46:49], v[186:189], v[196:199], v[46:49]
	v_mfma_f32_16x16x32_bf16 v[122:125], v[174:177], v[200:203], v[122:125]
	v_mfma_f32_16x16x32_bf16 v[122:125], v[178:181], v[204:207], v[122:125]
	v_mfma_f32_16x16x32_bf16 v[118:121], v[182:185], v[200:203], v[118:121]
	v_mfma_f32_16x16x32_bf16 v[118:121], v[186:189], v[204:207], v[118:121]
	v_mfma_f32_16x16x32_bf16 v[106:109], v[174:177], v[208:211], v[106:109]
	v_mfma_f32_16x16x32_bf16 v[106:109], v[178:181], v[212:215], v[106:109]
	v_mfma_f32_16x16x32_bf16 v[102:105], v[182:185], v[208:211], v[102:105]
	v_mfma_f32_16x16x32_bf16 v[102:105], v[186:189], v[212:215], v[102:105]
	v_mfma_f32_16x16x32_bf16 v[90:93], v[174:177], v[220:223], v[90:93]
	v_mfma_f32_16x16x32_bf16 v[90:93], v[178:181], v[224:227], v[90:93]
	v_mfma_f32_16x16x32_bf16 v[86:89], v[182:185], v[220:223], v[86:89]
	v_mfma_f32_16x16x32_bf16 v[86:89], v[186:189], v[224:227], v[86:89]
	s_setprio 0
	ds_read_b128 v[190:193], v171 offset:16384
	ds_read_b128 v[196:199], v171 offset:17408
	ds_read_b128 v[200:203], v171 offset:18432
	ds_read_b128 v[204:207], v171 offset:19456
	ds_read_b128 v[208:211], v171 offset:20480
	ds_read_b128 v[212:215], v171 offset:21504
	ds_read_b128 v[220:223], v171 offset:22528
	ds_read_b128 v[224:227], v171 offset:23552
	s_add_u32 vcc_lo, s90, 0x100000
	s_addc_u32 vcc_hi, s91, 0
	s_add_i32 m0, s27, 0x10000
	s_nop 0
	global_load_lds_dwordx4 v136, s[90:91]
	s_add_i32 m0, s27, 0x12000
	s_nop 0
	global_load_lds_dwordx4 v140, s[90:91]
	s_add_i32 m0, s27, 0x14000
	s_nop 0
	global_load_lds_dwordx4 v136, vcc
	s_add_i32 m0, s27, 0x16000
	s_nop 0
	global_load_lds_dwordx4 v140, vcc
	s_sleep 2
	s_waitcnt lgkmcnt(0)
	s_waitcnt vmcnt(6)
	s_barrier
; #define PG8_STAGE(bufoff, gbase, voff) do { _Pragma("unroll") for (int _i = 0; _i < 2; ++_i) \
;         __builtin_amdgcn_global_load_lds((const unsigned*)((const char*)(gbase) + (voff)[_i]), (PG8_LAS unsigned*)(lds + (bufoff) + ldsw + _i * 8192), 16, 0, 0); } while (0)
; #define PG8_LDA(dst, b, h) do { _Pragma("unroll") for (int m = 0; m < 4; ++m) _Pragma("unroll") for (int k = 0; k < 2; ++k) dst[m][k] = *(const PG8_LAS bf16x8*)(lds + PG8_SA(b, h) + aoff + m * 2048 + k * 1024); } while (0)
; #define PG8_LDB(dst, b, h) do { _Pragma("unroll") for (int n = 0; n < 2; ++n) _Pragma("unroll") for (int k = 0; k < 2; ++k) dst[n][k] = *(const PG8_LAS bf16x8*)(lds + PG8_SB(b, h) + boff + n * 2048 + k * 1024); } while (0)
; #define PG8_MMA(ai, bj, At, Bt) do { __builtin_amdgcn_s_setprio(1); _Pragma("unroll") for (int m = 0; m < 4; ++m) _Pragma("unroll") for (int n = 0; n < 2; ++n) _Pragma("unroll") for (int k = 0; k < 2; ++k) \
;         acc[ai][bj][m][n] = __builtin_amdgcn_mfma_f32_16x16x32_bf16(Bt[n][k], At[m][k], acc[ai][bj][m][n], 0, 0, 0); __builtin_amdgcn_s_setprio(0); } while (0)
; #define PG8_WAIT_V(n) asm volatile("s_waitcnt vmcnt(" #n ")" ::: "memory")
; #define PG8_WAIT_L(n) asm volatile("s_waitcnt lgkmcnt(" #n ")" ::: "memory")
; #define PG8_BAR __builtin_amdgcn_s_barrier()
; #define PG8_SCHED __builtin_amdgcn_sched_barrier(0)
; template <class Epi, class Sched, bool ALIGN_EPI = false, bool SP2 = false>
; __device__ __forceinline__ void gemm_phase(PG8_LAS unsigned char* lds, const Gemm g, const Sched& S, const Epi& E) {
;     ...
;             PG8_WAIT_V(8); PG8_WAIT_L(0); PG8_BAR; PG8_MMA(0, 0, At, B0); PG8_MMA(0, 1, At, B1); PG8_BAR; PG8_SCHED;
;             PG8_LDA(At, 0, 1); PG8_STAGE(PG8_SB(0, 0), b2, voffB); PG8_STAGE(PG8_SB(0, 1), b2 + hstep, voffB); PG8_STAGE(PG8_SA(0, 0), a2, voffA);
;             PG8_WAIT_V(8); PG8_WAIT_L(0); PG8_BAR; PG8_MMA(1, 0, At, B0); PG8_MMA(1, 1, At, B1); PG8_BAR; PG8_SCHED;
;             PG8_LDB(B0, 1, 0); PG8_LDB(B1, 1, 1); PG8_SCHED; PG8_LDA(At, 1, 0); PG8_STAGE(PG8_SA(0, 1), a2 + hstep, voffA);
	s_setprio 2
	v_mfma_f32_16x16x32_bf16 v[82:85], v[150:153], v[190:193], v[82:85]
	v_mfma_f32_16x16x32_bf16 v[82:85], v[154:157], v[196:199], v[82:85]
	v_mfma_f32_16x16x32_bf16 v[78:81], v[158:161], v[190:193], v[78:81]
	v_mfma_f32_16x16x32_bf16 v[78:81], v[162:165], v[196:199], v[78:81]
	v_mfma_f32_16x16x32_bf16 v[66:69], v[150:153], v[200:203], v[66:69]
	v_mfma_f32_16x16x32_bf16 v[66:69], v[154:157], v[204:207], v[66:69]
	v_mfma_f32_16x16x32_bf16 v[62:65], v[158:161], v[200:203], v[62:65]
	v_mfma_f32_16x16x32_bf16 v[62:65], v[162:165], v[204:207], v[62:65]
	v_mfma_f32_16x16x32_bf16 v[42:45], v[150:153], v[208:211], v[42:45]
	v_mfma_f32_16x16x32_bf16 v[42:45], v[154:157], v[212:215], v[42:45]
	v_mfma_f32_16x16x32_bf16 v[34:37], v[158:161], v[208:211], v[34:37]
	v_mfma_f32_16x16x32_bf16 v[34:37], v[162:165], v[212:215], v[34:37]
	v_mfma_f32_16x16x32_bf16 v[18:21], v[150:153], v[220:223], v[18:21]
	v_mfma_f32_16x16x32_bf16 v[18:21], v[154:157], v[224:227], v[18:21]
	v_mfma_f32_16x16x32_bf16 v[14:17], v[158:161], v[220:223], v[14:17]
	v_mfma_f32_16x16x32_bf16 v[14:17], v[162:165], v[224:227], v[14:17]
	v_mfma_f32_16x16x32_bf16 v[74:77], v[174:177], v[190:193], v[74:77]
	v_mfma_f32_16x16x32_bf16 v[74:77], v[178:181], v[196:199], v[74:77]
	v_mfma_f32_16x16x32_bf16 v[70:73], v[182:185], v[190:193], v[70:73]
	v_mfma_f32_16x16x32_bf16 v[70:73], v[186:189], v[196:199], v[70:73]
	v_mfma_f32_16x16x32_bf16 v[58:61], v[174:177], v[200:203], v[58:61]
	v_mfma_f32_16x16x32_bf16 v[58:61], v[178:181], v[204:207], v[58:61]
	v_mfma_f32_16x16x32_bf16 v[54:57], v[182:185], v[200:203], v[54:57]
	v_mfma_f32_16x16x32_bf16 v[54:57], v[186:189], v[204:207], v[54:57]
	v_mfma_f32_16x16x32_bf16 v[26:29], v[174:177], v[208:211], v[26:29]
	v_mfma_f32_16x16x32_bf16 v[26:29], v[178:181], v[212:215], v[26:29]
	v_mfma_f32_16x16x32_bf16 v[22:25], v[182:185], v[208:211], v[22:25]
	v_mfma_f32_16x16x32_bf16 v[22:25], v[186:189], v[212:215], v[22:25]
	v_mfma_f32_16x16x32_bf16 v[10:13], v[174:177], v[220:223], v[10:13]
	v_mfma_f32_16x16x32_bf16 v[10:13], v[178:181], v[224:227], v[10:13]
	v_mfma_f32_16x16x32_bf16 v[4:7], v[182:185], v[220:223], v[6:9]
	v_mfma_f32_16x16x32_bf16 v[4:7], v[186:189], v[224:227], v[4:7]
	s_setprio 0
	s_add_i32 s0, 0, 0x18000
	v_add_u32_e32 v3, s0, v167
	s_add_i32 s1, 0, 0x1c000
	ds_read_b128 v[150:153], v3
	ds_read_b128 v[154:157], v3 offset:1024
	ds_read_b128 v[158:161], v3 offset:2048
	ds_read_b128 v[162:165], v3 offset:3072
	v_add_u32_e32 v3, s1, v167
	ds_read_b128 v[174:177], v3
	ds_read_b128 v[178:181], v3 offset:1024
	ds_read_b128 v[182:185], v3 offset:2048
	ds_read_b128 v[186:189], v3 offset:3072
	ds_read_b128 v[190:193], v171 offset:32768
	ds_read_b128 v[196:199], v171 offset:33792
	ds_read_b128 v[200:203], v171 offset:34816
	ds_read_b128 v[204:207], v171 offset:35840
	ds_read_b128 v[208:211], v171 offset:36864
	ds_read_b128 v[212:215], v171 offset:37888
	ds_read_b128 v[220:223], v171 offset:38912
	ds_read_b128 v[224:227], v171 offset:39936
	s_add_u32 vcc_lo, s92, 0x100000
	s_addc_u32 vcc_hi, s93, 0
	s_mov_b32 m0, s27
	s_nop 0
	global_load_lds_dwordx4 v134, s[92:93]
	s_add_i32 m0, s27, 0x2000
	s_nop 0
	global_load_lds_dwordx4 v138, s[92:93]
	s_add_i32 m0, s27, 0x4000
	s_nop 0
	global_load_lds_dwordx4 v134, vcc
	s_add_i32 m0, s27, 0x6000
	s_nop 0
	global_load_lds_dwordx4 v138, vcc
	s_sleep 2
	s_waitcnt lgkmcnt(0)
	s_waitcnt vmcnt(8)
	s_barrier
; #define PG8_STAGE(bufoff, gbase, voff) do { _Pragma("unroll") for (int _i = 0; _i < 2; ++_i) \
;         __builtin_amdgcn_global_load_lds((const unsigned*)((const char*)(gbase) + (voff)[_i]), (PG8_LAS unsigned*)(lds + (bufoff) + ldsw + _i * 8192), 16, 0, 0); } while (0)
; #define PG8_LDA(dst, b, h) do { _Pragma("unroll") for (int m = 0; m < 4; ++m) _Pragma("unroll") for (int k = 0; k < 2; ++k) dst[m][k] = *(const PG8_LAS bf16x8*)(lds + PG8_SA(b, h) + aoff + m * 2048 + k * 1024); } while (0)
; #define PG8_LDB(dst, b, h) do { _Pragma("unroll") for (int n = 0; n < 2; ++n) _Pragma("unroll") for (int k = 0; k < 2; ++k) dst[n][k] = *(const PG8_LAS bf16x8*)(lds + PG8_SB(b, h) + boff + n * 2048 + k * 1024); } while (0)
; #define PG8_MMA(ai, bj, At, Bt) do { __builtin_amdgcn_s_setprio(1); _Pragma("unroll") for (int m = 0; m < 4; ++m) _Pragma("unroll") for (int n = 0; n < 2; ++n) _Pragma("unroll") for (int k = 0; k < 2; ++k) \
;         acc[ai][bj][m][n] = __builtin_amdgcn_mfma_f32_16x16x32_bf16(Bt[n][k], At[m][k], acc[ai][bj][m][n], 0, 0, 0); __builtin_amdgcn_s_setprio(0); } while (0)
; #define PG8_WAIT_V(n) asm volatile("s_waitcnt vmcnt(" #n ")" ::: "memory")
; #define PG8_WAIT_L(n) asm volatile("s_waitcnt lgkmcnt(" #n ")" ::: "memory")
; #define PG8_BAR __builtin_amdgcn_s_barrier()
; #define PG8_SCHED __builtin_amdgcn_sched_barrier(0)
; template <class Epi, class Sched, bool ALIGN_EPI = false, bool SP2 = false>
; __device__ __forceinline__ void gemm_phase(PG8_LAS unsigned char* lds, const Gemm g, const Sched& S, const Epi& E) {
;     ...
;             PG8_LDB(B0, 1, 0); PG8_LDB(B1, 1, 1); PG8_SCHED; PG8_LDA(At, 1, 0); PG8_STAGE(PG8_SA(0, 1), a2 + hstep, voffA);
;             PG8_WAIT_V(8); PG8_WAIT_L(0); PG8_BAR; PG8_MMA(0, 0, At, B0); PG8_MMA(0, 1, At, B1); PG8_BAR; PG8_SCHED;
;             PG8_LDA(At, 1, 1); PG8_STAGE(PG8_SB(1, 0), b3, voffB); PG8_STAGE(PG8_SB(1, 1), b3 + hstep, voffB); PG8_STAGE(PG8_SA(1, 0), a3, voffA);
;             PG8_WAIT_V(8); PG8_WAIT_L(0); PG8_BAR; PG8_MMA(1, 0, At, B0); PG8_MMA(1, 1, At, B1); PG8_BAR; PG8_SCHED;
	s_setprio 2
	v_mfma_f32_16x16x32_bf16 v[38:41], v[150:153], v[190:193], v[38:41]
	v_mfma_f32_16x16x32_bf16 v[38:41], v[154:157], v[196:199], v[38:41]
	v_mfma_f32_16x16x32_bf16 v[30:33], v[158:161], v[190:193], v[30:33]
	v_mfma_f32_16x16x32_bf16 v[30:33], v[162:165], v[196:199], v[30:33]
	v_mfma_f32_16x16x32_bf16 v[130:133], v[150:153], v[200:203], v[130:133]
	v_mfma_f32_16x16x32_bf16 v[130:133], v[154:157], v[204:207], v[130:133]
	v_mfma_f32_16x16x32_bf16 v[126:129], v[158:161], v[200:203], v[126:129]
	v_mfma_f32_16x16x32_bf16 v[126:129], v[162:165], v[204:207], v[126:129]
	v_mfma_f32_16x16x32_bf16 v[114:117], v[150:153], v[208:211], v[114:117]
	v_mfma_f32_16x16x32_bf16 v[114:117], v[154:157], v[212:215], v[114:117]
	v_mfma_f32_16x16x32_bf16 v[110:113], v[158:161], v[208:211], v[110:113]
	v_mfma_f32_16x16x32_bf16 v[110:113], v[162:165], v[212:215], v[110:113]
	v_mfma_f32_16x16x32_bf16 v[98:101], v[150:153], v[220:223], v[98:101]
	v_mfma_f32_16x16x32_bf16 v[98:101], v[154:157], v[224:227], v[98:101]
	v_mfma_f32_16x16x32_bf16 v[94:97], v[158:161], v[220:223], v[94:97]
	v_mfma_f32_16x16x32_bf16 v[94:97], v[162:165], v[224:227], v[94:97]
	v_mfma_f32_16x16x32_bf16 v[50:53], v[174:177], v[190:193], v[50:53]
	v_mfma_f32_16x16x32_bf16 v[50:53], v[178:181], v[196:199], v[50:53]
	v_mfma_f32_16x16x32_bf16 v[46:49], v[182:185], v[190:193], v[46:49]
	v_mfma_f32_16x16x32_bf16 v[46:49], v[186:189], v[196:199], v[46:49]
	v_mfma_f32_16x16x32_bf16 v[122:125], v[174:177], v[200:203], v[122:125]
	v_mfma_f32_16x16x32_bf16 v[122:125], v[178:181], v[204:207], v[122:125]
	v_mfma_f32_16x16x32_bf16 v[118:121], v[182:185], v[200:203], v[118:121]
	v_mfma_f32_16x16x32_bf16 v[118:121], v[186:189], v[204:207], v[118:121]
	v_mfma_f32_16x16x32_bf16 v[106:109], v[174:177], v[208:211], v[106:109]
	v_mfma_f32_16x16x32_bf16 v[106:109], v[178:181], v[212:215], v[106:109]
	v_mfma_f32_16x16x32_bf16 v[102:105], v[182:185], v[208:211], v[102:105]
	v_mfma_f32_16x16x32_bf16 v[102:105], v[186:189], v[212:215], v[102:105]
	v_mfma_f32_16x16x32_bf16 v[90:93], v[174:177], v[220:223], v[90:93]
	v_mfma_f32_16x16x32_bf16 v[90:93], v[178:181], v[224:227], v[90:93]
	v_mfma_f32_16x16x32_bf16 v[86:89], v[182:185], v[220:223], v[86:89]
	v_mfma_f32_16x16x32_bf16 v[86:89], v[186:189], v[224:227], v[86:89]
	s_setprio 0
	ds_read_b128 v[190:193], v171 offset:49152
	ds_read_b128 v[196:199], v171 offset:50176
	ds_read_b128 v[200:203], v171 offset:51200
	ds_read_b128 v[204:207], v171 offset:52224
	ds_read_b128 v[208:211], v171 offset:53248
	ds_read_b128 v[212:215], v171 offset:54272
	ds_read_b128 v[220:223], v171 offset:55296
	ds_read_b128 v[224:227], v171 offset:56320
	s_add_u32 s0, s90, 0x80
	s_addc_u32 s1, s91, 0
	s_add_u32 vcc_lo, s0, 0x100000
	s_addc_u32 vcc_hi, s1, 0
	s_add_i32 m0, s27, 0x18000
	s_nop 0
	global_load_lds_dwordx4 v136, s[0:1]
	s_add_i32 m0, s27, 0x1a000
	s_nop 0
	global_load_lds_dwordx4 v140, s[0:1]
	s_add_i32 m0, s27, 0x1c000
	s_nop 0
	global_load_lds_dwordx4 v136, vcc
	s_add_i32 m0, s27, 0x1e000
	s_nop 0
	global_load_lds_dwordx4 v140, vcc
	s_sleep 2
	s_waitcnt lgkmcnt(0)
	s_waitcnt vmcnt(6)
	s_barrier
	s_setprio 2
	v_mfma_f32_16x16x32_bf16 v[82:85], v[150:153], v[190:193], v[82:85]
	v_mfma_f32_16x16x32_bf16 v[82:85], v[154:157], v[196:199], v[82:85]
	v_mfma_f32_16x16x32_bf16 v[78:81], v[158:161], v[190:193], v[78:81]
	v_mfma_f32_16x16x32_bf16 v[78:81], v[162:165], v[196:199], v[78:81]
	v_mfma_f32_16x16x32_bf16 v[66:69], v[150:153], v[200:203], v[66:69]
	v_mfma_f32_16x16x32_bf16 v[66:69], v[154:157], v[204:207], v[66:69]
	v_mfma_f32_16x16x32_bf16 v[62:65], v[158:161], v[200:203], v[62:65]
	v_mfma_f32_16x16x32_bf16 v[62:65], v[162:165], v[204:207], v[62:65]
	v_mfma_f32_16x16x32_bf16 v[42:45], v[150:153], v[208:211], v[42:45]
	v_mfma_f32_16x16x32_bf16 v[42:45], v[154:157], v[212:215], v[42:45]
	v_mfma_f32_16x16x32_bf16 v[34:37], v[158:161], v[208:211], v[34:37]
	v_mfma_f32_16x16x32_bf16 v[34:37], v[162:165], v[212:215], v[34:37]
	v_mfma_f32_16x16x32_bf16 v[18:21], v[150:153], v[220:223], v[18:21]
	v_mfma_f32_16x16x32_bf16 v[18:21], v[154:157], v[224:227], v[18:21]
	v_mfma_f32_16x16x32_bf16 v[14:17], v[158:161], v[220:223], v[14:17]
	v_mfma_f32_16x16x32_bf16 v[14:17], v[162:165], v[224:227], v[14:17]
	v_mfma_f32_16x16x32_bf16 v[74:77], v[174:177], v[190:193], v[74:77]
	v_mfma_f32_16x16x32_bf16 v[74:77], v[178:181], v[196:199], v[74:77]
	v_mfma_f32_16x16x32_bf16 v[70:73], v[182:185], v[190:193], v[70:73]
	v_mfma_f32_16x16x32_bf16 v[70:73], v[186:189], v[196:199], v[70:73]
	v_mfma_f32_16x16x32_bf16 v[58:61], v[174:177], v[200:203], v[58:61]
	v_mfma_f32_16x16x32_bf16 v[58:61], v[178:181], v[204:207], v[58:61]
	v_mfma_f32_16x16x32_bf16 v[54:57], v[182:185], v[200:203], v[54:57]
	v_mfma_f32_16x16x32_bf16 v[54:57], v[186:189], v[204:207], v[54:57]
	v_mfma_f32_16x16x32_bf16 v[26:29], v[174:177], v[208:211], v[26:29]
	v_mfma_f32_16x16x32_bf16 v[26:29], v[178:181], v[212:215], v[26:29]
	v_mfma_f32_16x16x32_bf16 v[22:25], v[182:185], v[208:211], v[22:25]
	v_mfma_f32_16x16x32_bf16 v[22:25], v[186:189], v[212:215], v[22:25]
	v_mfma_f32_16x16x32_bf16 v[8:11], v[174:177], v[220:223], v[10:13]
	v_mfma_f32_16x16x32_bf16 v[10:13], v[178:181], v[224:227], v[8:11]
	v_mfma_f32_16x16x32_bf16 v[4:7], v[182:185], v[220:223], v[4:7]
	v_mfma_f32_16x16x32_bf16 v[6:9], v[186:189], v[224:227], v[4:7]
	s_setprio 0
	s_add_i32 s23, s23, 2
	s_add_u32 s88, s88, 0x100
	s_addc_u32 s89, s89, 0
	s_add_u32 s9, s9, 0x100
	s_addc_u32 s21, s21, 0
	s_cmp_gt_u32 s23, 61
	s_cbranch_scc0 .Lip_h1
